# conformer conv LayerNorm sums: the six-step ds_bpermute xor butterflies replaced by permlane32/16 swaps and DPP row rotations (same pair sums, no LDS round trips)
# speedup vs baseline: 1.0037x; 1.0026x over previous
; DI float sigmoidf_(float x) { return 1.f / (1.f + __expf(-x)); }
; DI float wave_sum(float v) {
; #pragma unroll
;   for (int o = 32; o > 0; o >>= 1) v += __shfl_xor(v, o);
;   return v;
; }
; DI void conv_item(const Params& p, int item, char* smem) {
;     ...
; #pragma unroll
;   for (int q = 0; q < 4; ++q) {
;     const int tl = wave * 4 + q;
;     float v[8];
;     float sum = 0.f;
; #pragma unroll
;     for (int i = 0; i < 8; ++i) { v[i] = cs[tl * 520 + lane + 64 * i]; sum += v[i]; }
;     float mean = wave_sum(sum) * (1.f / 512.f);
;     float sq = 0.f;
; #pragma unroll
;     for (int i = 0; i < 8; ++i) { float d = v[i] - mean; sq += d * d; }
;     float rstd = rsqrtf(wave_sum(sq) * (1.f / 512.f) + 1e-6f);
; #pragma unroll
;     for (int i = 0; i < 8; ++i) {
;       int c = lane + 64 * i;
;       float y = (v[i] - mean) * rstd * p.g_ln[c] + p.b_ln[c];
;       float sl = y * sigmoidf_(y);
;       CACT[((size_t)(b * 4096 + t0 + tl)) * 512 + c] = f2bf(sl);
;     }
.LBB0_743:
	s_or_b64 exec, exec, s[0:1]
	v_and_b32_e32 v26, 63, v0
	v_ashrrev_i32_e32 v44, 4, v0
	v_and_b32_e32 v0, 64, v156
	v_add_u32_e32 v0, 64, v0
	v_xor_b32_e32 v2, 32, v156
	v_and_b32_e32 v46, -4, v44
	v_cmp_lt_i32_e32 vcc, v2, v0
	v_or_b32_e32 v47, 1, v46
	v_lshlrev_b32_e32 v45, 2, v26
	v_cndmask_b32_e32 v2, v156, v2, vcc
	v_lshlrev_b32_e32 v38, 2, v2
	v_mul_lo_u32 v2, v46, s11
	v_mul_lo_u32 v12, v47, s11
	s_waitcnt vmcnt(0) lgkmcnt(0)
	v_add3_u32 v8, s33, v2, v45
	v_add3_u32 v14, s33, v12, v45
	ds_read2st64_b32 v[2:3], v8 offset0:4 offset1:5
	ds_read2st64_b32 v[4:5], v8 offset1:1
	ds_read2st64_b32 v[6:7], v8 offset0:2 offset1:3
	ds_read2st64_b32 v[8:9], v8 offset0:6 offset1:7
	ds_read2st64_b32 v[12:13], v14 offset1:1
	ds_read2st64_b32 v[16:17], v14 offset0:2 offset1:3
	ds_read2st64_b32 v[18:19], v14 offset0:4 offset1:5
	ds_read2st64_b32 v[20:21], v14 offset0:6 offset1:7
	s_waitcnt lgkmcnt(6)
	v_mov_b32_e32 v23, v4
	v_mov_b32_e32 v11, v2
	s_waitcnt lgkmcnt(4)
	v_mov_b32_e32 v15, v8
	s_waitcnt lgkmcnt(3)
	v_mov_b32_e32 v22, v12
	v_pk_add_f32 v[24:25], v[22:23], 0 op_sel_hi:[1,0]
	v_mov_b32_e32 v4, v13
	v_pk_add_f32 v[12:13], v[24:25], v[4:5]
	s_waitcnt lgkmcnt(2)
	v_mov_b32_e32 v24, v16
	v_mov_b32_e32 v25, v6
	v_pk_add_f32 v[12:13], v[12:13], v[24:25]
	v_mov_b32_e32 v6, v17
	v_pk_add_f32 v[12:13], v[12:13], v[6:7]
	s_waitcnt lgkmcnt(1)
	v_mov_b32_e32 v16, v18
	v_mov_b32_e32 v17, v2
	v_pk_add_f32 v[12:13], v[12:13], v[16:17]
	v_mov_b32_e32 v2, v19
	v_pk_add_f32 v[12:13], v[12:13], v[2:3]
	s_waitcnt lgkmcnt(0)
	v_mov_b32_e32 v16, v20
	v_mov_b32_e32 v17, v8
	v_pk_add_f32 v[12:13], v[12:13], v[16:17]
	v_mov_b32_e32 v8, v21
	v_pk_add_f32 v[12:13], v[12:13], v[8:9]
	v_mov_b32_e32 v17, v13
	s_nop 1
	v_permlane32_swap_b32_e32 v17, v13
	s_nop 1
	v_mov_b32_e32 v16, v12
	s_nop 1
	v_permlane32_swap_b32_e32 v16, v12
	s_nop 1
	v_xor_b32_e32 v10, 16, v156
	v_cmp_lt_i32_e32 vcc, v10, v0
	v_readlane_b32 s36, v253, 16
	v_readlane_b32 s44, v253, 24
	v_cndmask_b32_e32 v2, v156, v10, vcc
	v_lshlrev_b32_e32 v39, 2, v2
	s_waitcnt lgkmcnt(0)
	v_pk_add_f32 v[12:13], v[12:13], v[16:17]
	v_mov_b32_e32 v17, v13
	s_nop 1
	v_permlane16_swap_b32_e32 v17, v13
	s_nop 1
	v_mov_b32_e32 v16, v12
	s_nop 1
	v_permlane16_swap_b32_e32 v16, v12
	s_nop 1
	v_xor_b32_e32 v2, 8, v156
	v_cmp_lt_i32_e32 vcc, v2, v0
	v_readlane_b32 s45, v253, 25
	v_readlane_b32 s46, v253, 26
	v_cndmask_b32_e32 v2, v156, v2, vcc
	v_lshlrev_b32_e32 v40, 2, v2
	s_waitcnt lgkmcnt(0)
	v_pk_add_f32 v[12:13], v[12:13], v[16:17]
	s_nop 1
	v_mov_b32_dpp v17, v13 row_ror:8 row_mask:0xf bank_mask:0xf
	s_nop 0
	s_nop 1
	v_mov_b32_dpp v16, v12 row_ror:8 row_mask:0xf bank_mask:0xf
	s_nop 0
	v_xor_b32_e32 v2, 4, v156
	v_cmp_lt_i32_e32 vcc, v2, v0
	v_readlane_b32 s47, v253, 27
	global_load_dword v36, v45, s[44:45]
	s_nop 3
	global_load_dword v32, v45, s[46:47]
	global_load_dword v33, v45, s[44:45] offset:256
	global_load_dword v27, v45, s[46:47] offset:256
	v_cndmask_b32_e32 v2, v156, v2, vcc
	v_lshlrev_b32_e32 v41, 2, v2
	s_waitcnt lgkmcnt(0)
	v_pk_add_f32 v[12:13], v[12:13], v[16:17]
	s_nop 1
	v_mov_b32_dpp v17, v13 row_ror:4 row_mask:0xf bank_mask:0xf
	s_nop 0
	s_nop 1
	v_mov_b32_dpp v16, v12 row_ror:4 row_mask:0xf bank_mask:0xf
	s_nop 0
	v_xor_b32_e32 v2, 2, v156
	v_cmp_lt_i32_e32 vcc, v2, v0
	v_mov_b32_e32 v10, v3
	v_mov_b32_e32 v14, v9
	v_cndmask_b32_e32 v2, v156, v2, vcc
	v_lshlrev_b32_e32 v42, 2, v2
	s_waitcnt lgkmcnt(0)
	v_pk_add_f32 v[12:13], v[12:13], v[16:17]
	s_nop 1
	v_mov_b32_dpp v17, v13 row_ror:2 row_mask:0xf bank_mask:0xf
	s_nop 0
	s_nop 1
	v_mov_b32_dpp v16, v12 row_ror:2 row_mask:0xf bank_mask:0xf
	s_nop 0
	v_xor_b32_e32 v2, 1, v156
	v_cmp_lt_i32_e32 vcc, v2, v0
	v_mov_b32_e32 v28, v19
	v_mov_b32_e32 v29, v18
	v_cndmask_b32_e32 v0, v156, v2, vcc
	v_lshlrev_b32_e32 v43, 2, v0
	s_waitcnt lgkmcnt(0)
	v_pk_add_f32 v[2:3], v[12:13], v[16:17]
	s_nop 1
	v_mov_b32_dpp v9, v3 row_ror:1 row_mask:0xf bank_mask:0xf
	s_nop 0
	s_nop 1
	v_mov_b32_dpp v8, v2 row_ror:1 row_mask:0xf bank_mask:0xf
	s_nop 0
	v_or_b32_e32 v61, 2, v46
	v_or_b32_e32 v62, 3, v44
	v_readlane_b32 s37, v253, 17
	v_readlane_b32 s38, v253, 18
	s_waitcnt lgkmcnt(0)
	v_pk_add_f32 v[2:3], v[2:3], v[8:9]
	v_readlane_b32 s39, v253, 19
	v_pk_mul_f32 v[18:19], v[2:3], s[8:9] op_sel_hi:[1,0]
	v_pk_fma_f32 v[12:13], v[2:3], s[8:9], v[4:5] op_sel_hi:[1,0,1] neg_lo:[1,0,0] neg_hi:[1,0,0]
	v_pk_add_f32 v[16:17], v[14:15], v[18:19] op_sel:[0,1] neg_lo:[0,1] neg_hi:[0,1]
	v_pk_fma_f32 v[14:15], v[2:3], s[8:9], v[22:23] op_sel_hi:[1,0,1] neg_lo:[1,0,0] neg_hi:[1,0,0]
	v_pk_mul_f32 v[4:5], v[12:13], v[12:13]
	v_pk_add_f32 v[48:49], v[10:11], v[18:19] op_sel:[0,1] neg_lo:[0,1] neg_hi:[0,1]
	v_pk_fma_f32 v[4:5], v[14:15], v[14:15], v[4:5]
	v_pk_fma_f32 v[10:11], v[2:3], s[8:9], v[24:25] op_sel_hi:[1,0,1] neg_lo:[1,0,0] neg_hi:[1,0,0]
	v_pk_fma_f32 v[8:9], v[2:3], s[8:9], v[6:7] op_sel_hi:[1,0,1] neg_lo:[1,0,0] neg_hi:[1,0,0]
	v_pk_fma_f32 v[4:5], v[10:11], v[10:11], v[4:5]
	v_pk_add_f32 v[6:7], v[28:29], v[18:19] op_sel_hi:[1,0] neg_lo:[0,1] neg_hi:[0,1]
	v_pk_mul_f32 v[30:31], v[48:49], v[48:49]
	v_pk_fma_f32 v[2:3], v[8:9], v[8:9], v[4:5]
	v_pk_mul_f32 v[4:5], v[6:7], v[6:7]
	v_mov_b32_e32 v23, v31
	v_mov_b32_e32 v22, v5
	v_pk_add_f32 v[22:23], v[22:23], v[2:3]
	v_mov_b32_e32 v2, v21
	v_mov_b32_e32 v3, v20
	v_pk_add_f32 v[2:3], v[2:3], v[18:19] op_sel_hi:[1,0] neg_lo:[0,1] neg_hi:[0,1]
	v_pk_mul_f32 v[34:35], v[16:17], v[16:17]
	v_pk_mul_f32 v[18:19], v[2:3], v[2:3]
	v_mov_b32_e32 v5, v30
	v_pk_add_f32 v[4:5], v[4:5], v[22:23]
	v_mov_b32_e32 v20, v19
	v_mov_b32_e32 v21, v35
	v_pk_add_f32 v[4:5], v[20:21], v[4:5]
	v_mov_b32_e32 v19, v34
	v_pk_add_f32 v[4:5], v[18:19], v[4:5]
	v_mov_b32_e32 v19, v5
	s_nop 1
	v_permlane32_swap_b32_e32 v19, v5
	s_nop 1
	v_mov_b32_e32 v18, v4
	s_nop 1
	v_permlane32_swap_b32_e32 v18, v4
	s_nop 1
	global_load_dword v37, v45, s[44:45] offset:512
	global_load_dword v31, v45, s[46:47] offset:512
	global_load_dword v35, v45, s[44:45] offset:768
	global_load_dword v29, v45, s[46:47] offset:768
	v_readlane_b32 s40, v253, 20
	v_readlane_b32 s41, v253, 21
	s_waitcnt lgkmcnt(0)
; DI float sigmoidf_(float x) { return 1.f / (1.f + __expf(-x)); }
; DI float wave_sum(float v) {
; #pragma unroll
;   for (int o = 32; o > 0; o >>= 1) v += __shfl_xor(v, o);
;   return v;
; }
; DI void conv_item(const Params& p, int item, char* smem) {
;     ...
;     float mean = wave_sum(sum) * (1.f / 512.f);
;     float sq = 0.f;
; #pragma unroll
;     for (int i = 0; i < 8; ++i) { float d = v[i] - mean; sq += d * d; }
;     float rstd = rsqrtf(wave_sum(sq) * (1.f / 512.f) + 1e-6f);
; #pragma unroll
;     for (int i = 0; i < 8; ++i) {
;       int c = lane + 64 * i;
;       float y = (v[i] - mean) * rstd * p.g_ln[c] + p.b_ln[c];
;       float sl = y * sigmoidf_(y);
;       CACT[((size_t)(b * 4096 + t0 + tl)) * 512 + c] = f2bf(sl);
;     }
	v_pk_add_f32 v[4:5], v[4:5], v[18:19]
	v_mov_b32_e32 v19, v5
	s_nop 1
	v_permlane16_swap_b32_e32 v19, v5
	s_nop 1
	v_mov_b32_e32 v18, v4
	s_nop 1
	v_permlane16_swap_b32_e32 v18, v4
	s_nop 1
	v_readlane_b32 s42, v253, 22
	v_readlane_b32 s43, v253, 23
	v_readlane_b32 s48, v253, 28
	v_readlane_b32 s49, v253, 29
	s_waitcnt lgkmcnt(0)
	v_pk_add_f32 v[4:5], v[4:5], v[18:19]
	s_nop 1
	v_mov_b32_dpp v19, v5 row_ror:8 row_mask:0xf bank_mask:0xf
	s_nop 0
	s_nop 1
	v_mov_b32_dpp v18, v4 row_ror:8 row_mask:0xf bank_mask:0xf
	s_nop 0
	v_readlane_b32 s50, v253, 30
	v_readlane_b32 s51, v253, 31
	s_waitcnt lgkmcnt(0)
	v_pk_add_f32 v[4:5], v[4:5], v[18:19]
	s_nop 1
	v_mov_b32_dpp v19, v5 row_ror:4 row_mask:0xf bank_mask:0xf
	s_nop 0
	s_nop 1
	v_mov_b32_dpp v18, v4 row_ror:4 row_mask:0xf bank_mask:0xf
	s_nop 0
	s_waitcnt lgkmcnt(0)
	v_pk_add_f32 v[4:5], v[4:5], v[18:19]
	s_nop 1
	v_mov_b32_dpp v19, v5 row_ror:2 row_mask:0xf bank_mask:0xf
	s_nop 0
	s_nop 1
	v_mov_b32_dpp v18, v4 row_ror:2 row_mask:0xf bank_mask:0xf
	s_nop 0
	s_waitcnt lgkmcnt(0)
	v_pk_add_f32 v[4:5], v[4:5], v[18:19]
	s_nop 1
	v_mov_b32_dpp v19, v5 row_ror:1 row_mask:0xf bank_mask:0xf
	s_nop 0
	s_nop 1
	v_mov_b32_dpp v18, v4 row_ror:1 row_mask:0xf bank_mask:0xf
	s_nop 0
	s_waitcnt lgkmcnt(0)
	v_pk_add_f32 v[18:19], v[4:5], v[18:19]
	v_mov_b64_e32 v[4:5], s[10:11]
	v_pk_fma_f32 v[20:21], v[18:19], s[8:9], v[4:5] op_sel_hi:[1,0,0]
	v_add_u32_e32 v18, s12, v46
	v_mul_f32_e32 v0, 0x4b800000, v21
	v_cmp_gt_f32_e32 vcc, s20, v21
	v_ashrrev_i32_e32 v19, 31, v18
	v_lshlrev_b64 v[18:19], 10, v[18:19]
	v_cndmask_b32_e32 v0, v21, v0, vcc
	v_rsq_f32_e32 v0, v0
	v_lshl_add_u64 v[18:19], s[6:7], 0, v[18:19]
	v_mul_f32_e32 v21, 0x45800000, v0
	v_cndmask_b32_e32 v21, v0, v21, vcc
	v_mul_f32_e32 v0, v15, v21
	s_waitcnt vmcnt(6)
	v_fma_f32 v15, v36, v0, v32
	v_mul_f32_e32 v0, 0xbfb8aa3b, v15
	v_exp_f32_e32 v22, v0
	v_lshlrev_b32_e32 v0, 1, v26
	v_mul_f32_e32 v13, v13, v21
	s_waitcnt vmcnt(4)
	v_fma_f32 v13, v33, v13, v27
	v_add_f32_e32 v50, 1.0, v22
	global_load_dword v34, v45, s[44:45] offset:1024
	global_load_dword v28, v45, s[46:47] offset:1024
	global_load_dword v30, v45, s[44:45] offset:1280
	global_load_dword v25, v45, s[46:47] offset:1280
	global_load_dword v26, v45, s[44:45] offset:1536
	global_load_dword v23, v45, s[46:47] offset:1536
	global_load_dword v24, v45, s[44:45] offset:1792
	global_load_dword v22, v45, s[46:47] offset:1792
	v_div_scale_f32 v51, s[0:1], v50, v50, 1.0
	v_rcp_f32_e32 v52, v51
	v_lshl_add_u64 v[18:19], v[18:19], 0, v[0:1]
	v_mul_f32_e32 v11, v11, v21
	v_mul_f32_e32 v9, v9, v21
	v_fma_f32 v53, -v51, v52, 1.0
	v_fmac_f32_e32 v52, v53, v52
	v_div_scale_f32 v53, vcc, 1.0, v50, 1.0
	v_mul_f32_e32 v54, v53, v52
	v_fma_f32 v55, -v51, v54, v53
	v_fmac_f32_e32 v54, v55, v52
	v_fma_f32 v51, -v51, v54, v53
	v_mul_f32_e32 v53, 0xbfb8aa3b, v13
	v_exp_f32_e32 v53, v53
	v_div_fmas_f32 v51, v51, v52, v54
	v_div_fixup_f32 v50, v51, v50, 1.0
	v_mul_f32_e32 v15, v15, v50
	v_add_f32_e32 v50, 1.0, v53
	v_div_scale_f32 v51, s[0:1], v50, v50, 1.0
	v_rcp_f32_e32 v52, v51
	v_bfe_u32 v53, v15, 16, 1
	v_add3_u32 v15, v15, v53, s21
	global_store_short_d16_hi v[18:19], v15, off
	v_fma_f32 v15, -v51, v52, 1.0
	v_fmac_f32_e32 v52, v15, v52
	v_div_scale_f32 v15, vcc, 1.0, v50, 1.0
	v_mul_f32_e32 v53, v15, v52
	v_fma_f32 v54, -v51, v53, v15
	v_fmac_f32_e32 v53, v54, v52
	s_waitcnt vmcnt(11)
	v_fma_f32 v11, v37, v11, v31
	v_fma_f32 v15, -v51, v53, v15
	v_mul_f32_e32 v51, 0xbfb8aa3b, v11
	v_exp_f32_e32 v51, v51
	v_div_fmas_f32 v15, v15, v52, v53
	v_div_fixup_f32 v15, v15, v50, 1.0
	v_mul_f32_e32 v13, v13, v15
	v_add_f32_e32 v15, 1.0, v51
	v_div_scale_f32 v50, s[0:1], v15, v15, 1.0
	v_rcp_f32_e32 v51, v50
	v_bfe_u32 v52, v13, 16, 1
	v_add3_u32 v13, v13, v52, s21
	global_store_short_d16_hi v[18:19], v13, off offset:128
	v_fma_f32 v13, -v50, v51, 1.0
	v_fmac_f32_e32 v51, v13, v51
	v_div_scale_f32 v13, vcc, 1.0, v15, 1.0
	v_mul_f32_e32 v52, v13, v51
	v_fma_f32 v53, -v50, v52, v13
	v_fmac_f32_e32 v52, v53, v51
	s_waitcnt vmcnt(10)
	v_fma_f32 v9, v35, v9, v29
	v_fma_f32 v13, -v50, v52, v13
	v_mul_f32_e32 v50, 0xbfb8aa3b, v9
	v_exp_f32_e32 v50, v50
	v_div_fmas_f32 v13, v13, v51, v52
	v_div_fixup_f32 v13, v13, v15, 1.0
	v_mul_f32_e32 v11, v11, v13
	v_add_f32_e32 v13, 1.0, v50
	v_div_scale_f32 v15, s[0:1], v13, v13, 1.0
	v_rcp_f32_e32 v50, v15
	v_bfe_u32 v51, v11, 16, 1
	v_add3_u32 v11, v11, v51, s21
	global_store_short_d16_hi v[18:19], v11, off offset:256
	v_fma_f32 v11, -v15, v50, 1.0
	v_fmac_f32_e32 v50, v11, v50
	v_div_scale_f32 v11, vcc, 1.0, v13, 1.0
	v_mul_f32_e32 v51, v11, v50
	v_fma_f32 v52, -v15, v51, v11
	v_fmac_f32_e32 v51, v52, v50
	v_fma_f32 v11, -v15, v51, v11
	v_mul_f32_e32 v15, v49, v21
	s_waitcnt vmcnt(9)
	v_fma_f32 v15, v34, v15, v28
	v_mul_f32_e32 v49, 0xbfb8aa3b, v15
	v_exp_f32_e32 v49, v49
	v_div_fmas_f32 v11, v11, v50, v51
	v_div_fixup_f32 v11, v11, v13, 1.0
	v_mul_f32_e32 v9, v9, v11
	v_add_f32_e32 v11, 1.0, v49
	v_div_scale_f32 v13, s[0:1], v11, v11, 1.0
	v_rcp_f32_e32 v49, v13
	v_bfe_u32 v50, v9, 16, 1
	v_add3_u32 v9, v9, v50, s21
	global_store_short_d16_hi v[18:19], v9, off offset:384
	v_fma_f32 v9, -v13, v49, 1.0
	v_fmac_f32_e32 v49, v9, v49
	v_div_scale_f32 v9, vcc, 1.0, v11, 1.0
	v_mul_f32_e32 v50, v9, v49
	v_fma_f32 v51, -v13, v50, v9
	v_fmac_f32_e32 v50, v51, v49
	v_fma_f32 v9, -v13, v50, v9
	v_mul_f32_e32 v13, v48, v21
	s_waitcnt vmcnt(8)
; DI float sigmoidf_(float x) { return 1.f / (1.f + __expf(-x)); }
; DI void conv_item(const Params& p, int item, char* smem) {
;     ...
;     for (int i = 0; i < 8; ++i) { v[i] = cs[tl * 520 + lane + 64 * i]; sum += v[i]; }
;     ...
; #pragma unroll
;     for (int i = 0; i < 8; ++i) {
;       int c = lane + 64 * i;
;       float y = (v[i] - mean) * rstd * p.g_ln[c] + p.b_ln[c];
;       float sl = y * sigmoidf_(y);
;       CACT[((size_t)(b * 4096 + t0 + tl)) * 512 + c] = f2bf(sl);
;     }
	v_fma_f32 v13, v30, v13, v25
	v_mul_f32_e32 v48, 0xbfb8aa3b, v13
	v_exp_f32_e32 v48, v48
	v_div_fmas_f32 v9, v9, v49, v50
	v_div_fixup_f32 v9, v9, v11, 1.0
	v_mul_f32_e32 v9, v15, v9
	v_add_f32_e32 v11, 1.0, v48
	v_div_scale_f32 v15, s[0:1], v11, v11, 1.0
	v_rcp_f32_e32 v48, v15
	v_bfe_u32 v49, v9, 16, 1
	v_add3_u32 v9, v9, v49, s21
	global_store_short_d16_hi v[18:19], v9, off offset:512
	v_fma_f32 v9, -v15, v48, 1.0
	v_fmac_f32_e32 v48, v9, v48
	v_div_scale_f32 v9, vcc, 1.0, v11, 1.0
	v_mul_f32_e32 v49, v9, v48
	v_fma_f32 v50, -v15, v49, v9
	v_fmac_f32_e32 v49, v50, v48
	v_fma_f32 v9, -v15, v49, v9
	v_mul_f32_e32 v15, v17, v21
	s_waitcnt vmcnt(7)
	v_fma_f32 v15, v26, v15, v23
	v_mul_f32_e32 v17, 0xbfb8aa3b, v15
	v_exp_f32_e32 v17, v17
	v_div_fmas_f32 v9, v9, v48, v49
	v_div_fixup_f32 v9, v9, v11, 1.0
	v_mul_f32_e32 v9, v13, v9
	v_add_f32_e32 v11, 1.0, v17
	v_div_scale_f32 v13, s[0:1], v11, v11, 1.0
	v_rcp_f32_e32 v17, v13
	v_bfe_u32 v48, v9, 16, 1
	v_add3_u32 v9, v9, v48, s21
	global_store_short_d16_hi v[18:19], v9, off offset:640
	v_fma_f32 v9, -v13, v17, 1.0
	v_fmac_f32_e32 v17, v9, v17
	v_div_scale_f32 v9, vcc, 1.0, v11, 1.0
	v_mul_f32_e32 v48, v9, v17
	v_fma_f32 v49, -v13, v48, v9
	v_fmac_f32_e32 v48, v49, v17
	v_fma_f32 v9, -v13, v48, v9
	v_mul_f32_e32 v13, v16, v21
	s_waitcnt vmcnt(6)
	v_fma_f32 v13, v13, v24, v22
	v_mul_f32_e32 v16, 0xbfb8aa3b, v13
	v_exp_f32_e32 v16, v16
	v_div_fmas_f32 v9, v9, v17, v48
	v_div_fixup_f32 v9, v9, v11, 1.0
	v_mul_f32_e32 v9, v15, v9
	v_add_f32_e32 v11, 1.0, v16
	v_div_scale_f32 v15, s[0:1], v11, v11, 1.0
	v_rcp_f32_e32 v16, v15
	v_bfe_u32 v17, v9, 16, 1
	v_add3_u32 v9, v9, v17, s21
	global_store_short_d16_hi v[18:19], v9, off offset:768
	v_fma_f32 v9, -v15, v16, 1.0
	v_fmac_f32_e32 v16, v9, v16
	v_div_scale_f32 v9, vcc, 1.0, v11, 1.0
	v_mul_f32_e32 v17, v9, v16
	v_fma_f32 v21, -v15, v17, v9
	v_fmac_f32_e32 v17, v21, v16
	v_fma_f32 v9, -v15, v17, v9
	v_div_fmas_f32 v9, v9, v16, v17
	v_mul_f32_e32 v15, 0x4b800000, v20
	v_cmp_gt_f32_e32 vcc, s20, v20
	v_div_fixup_f32 v9, v9, v11, 1.0
	v_mul_f32_e32 v9, v13, v9
	v_cndmask_b32_e32 v15, v20, v15, vcc
	v_rsq_f32_e32 v15, v15
	v_bfe_u32 v11, v9, 16, 1
	v_add3_u32 v9, v9, v11, s21
	global_store_short_d16_hi v[18:19], v9, off offset:896
	v_mul_f32_e32 v13, 0x45800000, v15
	v_cndmask_b32_e32 v60, v15, v13, vcc
	v_mul_f32_e32 v13, v14, v60
	v_fma_f32 v13, v36, v13, v32
	v_mul_f32_e32 v14, 0xbfb8aa3b, v13
	v_exp_f32_e32 v15, v14
	v_mul_f32_e32 v12, v12, v60
	v_add_u32_e32 v14, s12, v47
	v_mul_f32_e32 v10, v10, v60
	v_add_f32_e32 v9, 1.0, v15
	v_div_scale_f32 v11, s[0:1], v9, v9, 1.0
	v_rcp_f32_e32 v16, v11
	v_ashrrev_i32_e32 v15, 31, v14
	v_lshlrev_b64 v[14:15], 10, v[14:15]
	v_lshl_add_u64 v[14:15], s[6:7], 0, v[14:15]
	v_fma_f32 v17, -v11, v16, 1.0
	v_fmac_f32_e32 v16, v17, v16
	v_div_scale_f32 v17, vcc, 1.0, v9, 1.0
	v_mul_f32_e32 v18, v17, v16
	v_fma_f32 v19, -v11, v18, v17
	v_fmac_f32_e32 v18, v19, v16
	v_fma_f32 v11, -v11, v18, v17
	v_div_fmas_f32 v11, v11, v16, v18
	v_fma_f32 v16, v33, v12, v27
	v_mul_f32_e32 v12, 0xbfb8aa3b, v16
	v_exp_f32_e32 v12, v12
	v_div_fixup_f32 v9, v11, v9, 1.0
	v_mul_f32_e32 v9, v13, v9
	v_bfe_u32 v11, v9, 16, 1
	v_add_f32_e32 v17, 1.0, v12
	v_div_scale_f32 v18, s[0:1], v17, v17, 1.0
	v_rcp_f32_e32 v19, v18
	v_add3_u32 v9, v9, v11, s21
	v_lshl_add_u64 v[12:13], v[14:15], 0, v[0:1]
	global_store_short_d16_hi v[12:13], v9, off
	v_fma_f32 v9, -v18, v19, 1.0
	v_fmac_f32_e32 v19, v9, v19
	v_div_scale_f32 v9, vcc, 1.0, v17, 1.0
	v_mul_f32_e32 v11, v9, v19
	v_fma_f32 v14, -v18, v11, v9
	v_fma_f32 v10, v37, v10, v31
	v_fmac_f32_e32 v11, v14, v19
	v_mul_f32_e32 v14, 0xbfb8aa3b, v10
	v_exp_f32_e32 v14, v14
	v_fma_f32 v9, -v18, v11, v9
	v_div_fmas_f32 v9, v9, v19, v11
	v_div_fixup_f32 v9, v9, v17, 1.0
	v_add_f32_e32 v11, 1.0, v14
	v_div_scale_f32 v14, s[0:1], v11, v11, 1.0
	v_rcp_f32_e32 v15, v14
	v_mul_f32_e32 v9, v16, v9
	v_bfe_u32 v16, v9, 16, 1
	v_add3_u32 v9, v9, v16, s21
	global_store_short_d16_hi v[12:13], v9, off offset:128
	v_fma_f32 v9, -v14, v15, 1.0
	v_fmac_f32_e32 v15, v9, v15
	v_div_scale_f32 v9, vcc, 1.0, v11, 1.0
	v_mul_f32_e32 v16, v9, v15
	v_fma_f32 v17, -v14, v16, v9
	v_mul_f32_e32 v8, v8, v60
	v_fmac_f32_e32 v16, v17, v15
	v_fma_f32 v8, v35, v8, v29
	v_fma_f32 v9, -v14, v16, v9
	v_mul_f32_e32 v14, 0xbfb8aa3b, v8
	v_exp_f32_e32 v14, v14
	v_div_fmas_f32 v9, v9, v15, v16
	v_div_fixup_f32 v9, v9, v11, 1.0
	v_mul_f32_e32 v9, v10, v9
	v_add_f32_e32 v10, 1.0, v14
	v_div_scale_f32 v11, s[0:1], v10, v10, 1.0
	v_rcp_f32_e32 v14, v11
	v_bfe_u32 v15, v9, 16, 1
	v_add3_u32 v9, v9, v15, s21
	global_store_short_d16_hi v[12:13], v9, off offset:256
	v_fma_f32 v9, -v11, v14, 1.0
	v_fmac_f32_e32 v14, v9, v14
	v_div_scale_f32 v9, vcc, 1.0, v10, 1.0
	v_mul_f32_e32 v15, v9, v14
	v_fma_f32 v16, -v11, v15, v9
	v_mul_f32_e32 v7, v7, v60
	v_fmac_f32_e32 v15, v16, v14
	v_fma_f32 v7, v34, v7, v28
	v_fma_f32 v9, -v11, v15, v9
	v_mul_f32_e32 v11, 0xbfb8aa3b, v7
	v_exp_f32_e32 v11, v11
	v_div_fmas_f32 v9, v9, v14, v15
	v_div_fixup_f32 v9, v9, v10, 1.0
	v_mul_f32_e32 v8, v8, v9
	v_add_f32_e32 v9, 1.0, v11
	v_div_scale_f32 v10, s[0:1], v9, v9, 1.0
	v_rcp_f32_e32 v11, v10
	v_bfe_u32 v14, v8, 16, 1
	v_add3_u32 v8, v8, v14, s21
	global_store_short_d16_hi v[12:13], v8, off offset:384
	v_fma_f32 v8, -v10, v11, 1.0
	v_fmac_f32_e32 v11, v8, v11
	v_div_scale_f32 v8, vcc, 1.0, v9, 1.0
	v_mul_f32_e32 v6, v6, v60
	v_mul_f32_e32 v14, v8, v11
	v_fma_f32 v16, v30, v6, v25
	v_fma_f32 v15, -v10, v14, v8
	v_mul_f32_e32 v6, 0xbfb8aa3b, v16
	v_fmac_f32_e32 v14, v15, v11
	v_exp_f32_e32 v6, v6
	v_fma_f32 v8, -v10, v14, v8
	v_div_fmas_f32 v8, v8, v11, v14
	v_div_fixup_f32 v8, v8, v9, 1.0
	v_mul_f32_e32 v7, v7, v8
	v_add_f32_e32 v8, 1.0, v6
	v_div_scale_f32 v6, s[0:1], v8, v8, 1.0
	v_rcp_f32_e32 v9, v6
	v_bfe_u32 v10, v7, 16, 1
	v_add3_u32 v7, v7, v10, s21
	global_store_short_d16_hi v[12:13], v7, off offset:512
	v_fma_f32 v7, -v6, v9, 1.0
	v_fmac_f32_e32 v9, v7, v9
	v_div_scale_f32 v7, vcc, 1.0, v8, 1.0
	v_mul_f32_e32 v10, v7, v9
	v_fma_f32 v11, -v6, v10, v7
	v_fmac_f32_e32 v10, v11, v9
	v_fma_f32 v6, -v6, v10, v7
	v_div_fmas_f32 v9, v6, v9, v10
	v_mul_lo_u32 v6, v61, s11
	v_mul_lo_u32 v18, v62, s11
	v_add3_u32 v14, s33, v6, v45
	v_add3_u32 v48, s33, v18, v45
	ds_read2st64_b32 v[6:7], v14 offset0:4 offset1:5
	v_div_fixup_f32 v20, v9, v8, 1.0
	ds_read2st64_b32 v[8:9], v14 offset1:1
	ds_read2st64_b32 v[10:11], v14 offset0:2 offset1:3
	ds_read2st64_b32 v[14:15], v14 offset0:6 offset1:7
	ds_read2st64_b32 v[18:19], v48 offset1:1
	ds_read2st64_b32 v[44:45], v48 offset0:2 offset1:3
	ds_read2st64_b32 v[46:47], v48 offset0:4 offset1:5
	ds_read2st64_b32 v[48:49], v48 offset0:6 offset1:7
	s_waitcnt lgkmcnt(6)
; DI float wave_sum(float v) {
; #pragma unroll
;   for (int o = 32; o > 0; o >>= 1) v += __shfl_xor(v, o);
;   return v;
; }
; DI void conv_item(const Params& p, int item, char* smem) {
;     ...
;     float sum = 0.f;
; #pragma unroll
;     for (int i = 0; i < 8; ++i) { v[i] = cs[tl * 520 + lane + 64 * i]; sum += v[i]; }
;     float mean = wave_sum(sum) * (1.f / 512.f);
;     float sq = 0.f;
; #pragma unroll
;     for (int i = 0; i < 8; ++i) { float d = v[i] - mean; sq += d * d; }
;     float rstd = rsqrtf(wave_sum(sq) * (1.f / 512.f) + 1e-6f);
	v_mov_b32_e32 v51, v8
	v_mov_b32_e32 v17, v6
	s_waitcnt lgkmcnt(4)
	v_mov_b32_e32 v21, v14
	s_waitcnt lgkmcnt(3)
	v_mov_b32_e32 v50, v18
	v_pk_add_f32 v[52:53], v[50:51], 0 op_sel_hi:[1,0]
	v_mov_b32_e32 v8, v19
	v_pk_add_f32 v[18:19], v[52:53], v[8:9]
	s_waitcnt lgkmcnt(2)
	v_mov_b32_e32 v52, v44
	v_mov_b32_e32 v53, v10
	v_pk_add_f32 v[18:19], v[18:19], v[52:53]
	v_mov_b32_e32 v10, v45
	v_pk_add_f32 v[18:19], v[18:19], v[10:11]
	s_waitcnt lgkmcnt(1)
	v_mov_b32_e32 v44, v46
	v_mov_b32_e32 v45, v6
	v_pk_add_f32 v[18:19], v[18:19], v[44:45]
	v_mov_b32_e32 v6, v47
	v_pk_add_f32 v[18:19], v[18:19], v[6:7]
	s_waitcnt lgkmcnt(0)
	v_mov_b32_e32 v44, v48
	v_mov_b32_e32 v45, v14
	v_pk_add_f32 v[18:19], v[18:19], v[44:45]
	v_mov_b32_e32 v14, v49
	v_pk_add_f32 v[18:19], v[18:19], v[14:15]
	v_mov_b32_e32 v45, v19
	s_nop 1
	v_permlane32_swap_b32_e32 v45, v19
	s_nop 1
	v_mov_b32_e32 v44, v18
	s_nop 1
	v_permlane32_swap_b32_e32 v44, v18
	s_nop 1
	v_mul_f32_e32 v6, v16, v20
	v_bfe_u32 v14, v6, 16, 1
	v_mul_f32_e32 v3, v3, v60
	v_add3_u32 v6, v6, v14, s21
	s_waitcnt lgkmcnt(0)
	v_pk_add_f32 v[18:19], v[18:19], v[44:45]
	v_mov_b32_e32 v45, v19
	s_nop 1
	v_permlane16_swap_b32_e32 v45, v19
	s_nop 1
	v_mov_b32_e32 v44, v18
	s_nop 1
	v_permlane16_swap_b32_e32 v44, v18
	s_nop 1
	v_fma_f32 v3, v26, v3, v23
	global_store_short_d16_hi v[12:13], v6, off offset:640
	v_mul_f32_e32 v6, 0xbfb8aa3b, v3
	v_exp_f32_e32 v6, v6
	s_waitcnt lgkmcnt(0)
	v_pk_add_f32 v[18:19], v[18:19], v[44:45]
	s_nop 1
	v_mov_b32_dpp v45, v19 row_ror:8 row_mask:0xf bank_mask:0xf
	s_nop 0
	s_nop 1
	v_mov_b32_dpp v44, v18 row_ror:8 row_mask:0xf bank_mask:0xf
	s_nop 0
	v_add_f32_e32 v63, 1.0, v6
	v_div_scale_f32 v6, s[0:1], v63, v63, 1.0
	v_rcp_f32_e32 v64, v6
	s_waitcnt lgkmcnt(0)
	v_pk_add_f32 v[18:19], v[18:19], v[44:45]
	s_nop 1
	v_mov_b32_dpp v45, v19 row_ror:4 row_mask:0xf bank_mask:0xf
	s_nop 0
	s_nop 1
	v_mov_b32_dpp v44, v18 row_ror:4 row_mask:0xf bank_mask:0xf
	s_nop 0
	v_fma_f32 v14, -v6, v64, 1.0
	v_fmac_f32_e32 v64, v14, v64
	v_div_scale_f32 v14, vcc, 1.0, v63, 1.0
	s_waitcnt lgkmcnt(0)
	v_pk_add_f32 v[18:19], v[18:19], v[44:45]
	s_nop 1
	v_mov_b32_dpp v45, v19 row_ror:2 row_mask:0xf bank_mask:0xf
	s_nop 0
	s_nop 1
	v_mov_b32_dpp v44, v18 row_ror:2 row_mask:0xf bank_mask:0xf
	s_nop 0
	v_mul_f32_e32 v65, v14, v64
	v_fma_f32 v16, -v6, v65, v14
	v_fmac_f32_e32 v65, v16, v64
	v_fma_f32 v66, -v6, v65, v14
	s_waitcnt lgkmcnt(0)
	v_pk_add_f32 v[18:19], v[18:19], v[44:45]
	s_nop 1
	v_mov_b32_dpp v45, v19 row_ror:1 row_mask:0xf bank_mask:0xf
	s_nop 0
	s_nop 1
	v_mov_b32_dpp v44, v18 row_ror:1 row_mask:0xf bank_mask:0xf
	s_nop 0
	v_mov_b32_e32 v16, v7
	v_mov_b32_e32 v6, v47
	v_mov_b32_e32 v7, v46
	v_mov_b32_e32 v20, v15
	s_waitcnt lgkmcnt(0)
	v_pk_add_f32 v[44:45], v[18:19], v[44:45]
	v_mul_f32_e32 v2, v2, v60
	v_pk_mul_f32 v[46:47], v[44:45], s[8:9] op_sel_hi:[1,0]
	v_pk_fma_f32 v[18:19], v[44:45], s[8:9], v[50:51] op_sel_hi:[1,0,1] neg_lo:[1,0,0] neg_hi:[1,0,0]
	v_pk_add_f32 v[54:55], v[16:17], v[46:47] op_sel:[0,1] neg_lo:[0,1] neg_hi:[0,1]
	v_pk_fma_f32 v[16:17], v[44:45], s[8:9], v[8:9] op_sel_hi:[1,0,1] neg_lo:[1,0,0] neg_hi:[1,0,0]
	v_pk_fma_f32 v[14:15], v[44:45], s[8:9], v[52:53] op_sel_hi:[1,0,1] neg_lo:[1,0,0] neg_hi:[1,0,0]
	v_pk_mul_f32 v[8:9], v[16:17], v[16:17]
	v_pk_fma_f32 v[10:11], v[44:45], s[8:9], v[10:11] op_sel_hi:[1,0,1] neg_lo:[1,0,0] neg_hi:[1,0,0]
	v_pk_fma_f32 v[8:9], v[18:19], v[18:19], v[8:9]
	v_pk_mul_f32 v[56:57], v[54:55], v[54:55]
	v_pk_fma_f32 v[8:9], v[14:15], v[14:15], v[8:9]
	v_pk_add_f32 v[20:21], v[20:21], v[46:47] op_sel:[0,1] neg_lo:[0,1] neg_hi:[0,1]
	v_pk_fma_f32 v[44:45], v[10:11], v[10:11], v[8:9]
	v_pk_add_f32 v[8:9], v[6:7], v[46:47] op_sel_hi:[1,0] neg_lo:[0,1] neg_hi:[0,1]
	v_mov_b32_e32 v7, v57
	v_pk_mul_f32 v[50:51], v[8:9], v[8:9]
	v_pk_mul_f32 v[58:59], v[20:21], v[20:21]
	v_mov_b32_e32 v6, v51
	v_pk_add_f32 v[44:45], v[6:7], v[44:45]
	v_mov_b32_e32 v6, v49
	v_mov_b32_e32 v7, v48
	v_pk_add_f32 v[6:7], v[6:7], v[46:47] op_sel_hi:[1,0] neg_lo:[0,1] neg_hi:[0,1]
	v_mov_b32_e32 v51, v56
	v_pk_mul_f32 v[46:47], v[6:7], v[6:7]
	v_pk_add_f32 v[44:45], v[50:51], v[44:45]
	v_mov_b32_e32 v48, v47
	v_mov_b32_e32 v49, v59
	v_pk_add_f32 v[44:45], v[48:49], v[44:45]
	v_mov_b32_e32 v47, v58
	v_pk_add_f32 v[44:45], v[46:47], v[44:45]
	v_mov_b32_e32 v47, v45
	s_nop 1
	v_permlane32_swap_b32_e32 v47, v45
	s_nop 1
	v_mov_b32_e32 v46, v44
	s_nop 1
	v_permlane32_swap_b32_e32 v46, v44
	s_nop 1
	v_div_fmas_f32 v38, v66, v64, v65
	v_fma_f32 v50, v24, v2, v22
	v_div_fixup_f32 v38, v38, v63, 1.0
	v_mul_f32_e32 v2, 0xbfb8aa3b, v50
	s_waitcnt lgkmcnt(0)
	v_pk_add_f32 v[44:45], v[44:45], v[46:47]
	v_mov_b32_e32 v47, v45
	s_nop 1
	v_permlane16_swap_b32_e32 v47, v45
	s_nop 1
	v_mov_b32_e32 v46, v44
	s_nop 1
	v_permlane16_swap_b32_e32 v46, v44
	s_nop 1
	v_mul_f32_e32 v48, v3, v38
	v_exp_f32_e32 v51, v2
	v_bfe_u32 v49, v48, 16, 1
	s_waitcnt lgkmcnt(0)
	v_pk_add_f32 v[2:3], v[44:45], v[46:47]
	s_nop 1
	v_mov_b32_dpp v39, v3 row_ror:8 row_mask:0xf bank_mask:0xf
	s_nop 0
	s_nop 1
	v_mov_b32_dpp v38, v2 row_ror:8 row_mask:0xf bank_mask:0xf
	s_nop 0
	v_add_f32_e32 v40, 1.0, v51
	v_div_scale_f32 v44, s[0:1], v40, v40, 1.0
	v_rcp_f32_e32 v45, v44
	s_waitcnt lgkmcnt(0)
	v_pk_add_f32 v[2:3], v[2:3], v[38:39]
	s_nop 1
	v_mov_b32_dpp v39, v3 row_ror:4 row_mask:0xf bank_mask:0xf
	s_nop 0
	s_nop 1
	v_mov_b32_dpp v38, v2 row_ror:4 row_mask:0xf bank_mask:0xf
	s_nop 0
	v_add3_u32 v41, v48, v49, s21
	global_store_short_d16_hi v[12:13], v41, off offset:768
	v_fma_f32 v41, -v44, v45, 1.0
	v_fmac_f32_e32 v45, v41, v45
	s_waitcnt lgkmcnt(0)
; DI float sigmoidf_(float x) { return 1.f / (1.f + __expf(-x)); }
; DI float wave_sum(float v) {
; #pragma unroll
;   for (int o = 32; o > 0; o >>= 1) v += __shfl_xor(v, o);
;   return v;
; }
; DI void conv_item(const Params& p, int item, char* smem) {
;     ...
;     for (int i = 0; i < 8; ++i) { float d = v[i] - mean; sq += d * d; }
;     float rstd = rsqrtf(wave_sum(sq) * (1.f / 512.f) + 1e-6f);
; #pragma unroll
;     for (int i = 0; i < 8; ++i) {
;       int c = lane + 64 * i;
;       float y = (v[i] - mean) * rstd * p.g_ln[c] + p.b_ln[c];
;       float sl = y * sigmoidf_(y);
;       CACT[((size_t)(b * 4096 + t0 + tl)) * 512 + c] = f2bf(sl);
;     }
	v_pk_add_f32 v[2:3], v[2:3], v[38:39]
	s_nop 1
	v_mov_b32_dpp v39, v3 row_ror:2 row_mask:0xf bank_mask:0xf
	s_nop 0
	s_nop 1
	v_mov_b32_dpp v38, v2 row_ror:2 row_mask:0xf bank_mask:0xf
	s_nop 0
	v_div_scale_f32 v41, vcc, 1.0, v40, 1.0
	v_mul_f32_e32 v42, v41, v45
	v_fma_f32 v46, -v44, v42, v41
	s_waitcnt lgkmcnt(0)
	v_pk_add_f32 v[2:3], v[2:3], v[38:39]
	s_nop 1
	v_mov_b32_dpp v39, v3 row_ror:1 row_mask:0xf bank_mask:0xf
	s_nop 0
	s_nop 1
	v_mov_b32_dpp v38, v2 row_ror:1 row_mask:0xf bank_mask:0xf
	s_nop 0
	v_fmac_f32_e32 v42, v46, v45
	v_fma_f32 v41, -v44, v42, v41
	v_div_fmas_f32 v41, v41, v45, v42
	v_div_fixup_f32 v40, v41, v40, 1.0
	s_waitcnt lgkmcnt(0)
	v_pk_add_f32 v[2:3], v[2:3], v[38:39]
	s_nop 0
	v_pk_fma_f32 v[2:3], v[2:3], s[8:9], v[4:5] op_sel_hi:[1,0,0]
	s_nop 0
	v_mul_f32_e32 v4, 0x4b800000, v3
	v_cmp_gt_f32_e32 vcc, s20, v3
	s_nop 1
	v_cndmask_b32_e32 v3, v3, v4, vcc
	v_rsq_f32_e32 v3, v3
	v_mul_f32_e32 v4, v50, v40
	v_bfe_u32 v5, v4, 16, 1
	v_add3_u32 v4, v4, v5, s21
	v_mul_f32_e32 v5, 0x45800000, v3
	v_cndmask_b32_e32 v3, v3, v5, vcc
	v_mul_f32_e32 v5, v19, v3
	v_fma_f32 v19, v36, v5, v32
	v_mul_f32_e32 v5, 0xbfb8aa3b, v19
	v_exp_f32_e32 v38, v5
	global_store_short_d16_hi v[12:13], v4, off offset:896
	v_mul_f32_e32 v17, v17, v3
	v_fma_f32 v17, v33, v17, v27
	v_add_f32_e32 v12, 1.0, v38
	v_div_scale_f32 v13, s[0:1], v12, v12, 1.0
	v_rcp_f32_e32 v38, v13
	v_add_u32_e32 v4, s12, v61
	v_ashrrev_i32_e32 v5, 31, v4
	v_lshlrev_b64 v[4:5], 10, v[4:5]
	v_fma_f32 v39, -v13, v38, 1.0
	v_fmac_f32_e32 v38, v39, v38
	v_div_scale_f32 v39, vcc, 1.0, v12, 1.0
	v_mul_f32_e32 v40, v39, v38
	v_fma_f32 v41, -v13, v40, v39
	v_fmac_f32_e32 v40, v41, v38
	v_fma_f32 v13, -v13, v40, v39
	v_mul_f32_e32 v39, 0xbfb8aa3b, v17
	v_exp_f32_e32 v39, v39
	v_div_fmas_f32 v13, v13, v38, v40
	v_div_fixup_f32 v12, v13, v12, 1.0
	v_mul_f32_e32 v12, v19, v12
	v_add_f32_e32 v13, 1.0, v39
	v_div_scale_f32 v19, s[0:1], v13, v13, 1.0
	v_rcp_f32_e32 v38, v19
	v_lshl_add_u64 v[4:5], s[6:7], 0, v[4:5]
	v_bfe_u32 v39, v12, 16, 1
	v_lshl_add_u64 v[4:5], v[4:5], 0, v[0:1]
	v_add3_u32 v12, v12, v39, s21
	global_store_short_d16_hi v[4:5], v12, off
	v_fma_f32 v12, -v19, v38, 1.0
	v_fmac_f32_e32 v38, v12, v38
	v_div_scale_f32 v12, vcc, 1.0, v13, 1.0
	v_mul_f32_e32 v39, v12, v38
	v_fma_f32 v40, -v19, v39, v12
	v_mul_f32_e32 v15, v15, v3
	v_fmac_f32_e32 v39, v40, v38
	v_fma_f32 v15, v37, v15, v31
	v_fma_f32 v12, -v19, v39, v12
	v_mul_f32_e32 v19, 0xbfb8aa3b, v15
	v_exp_f32_e32 v19, v19
	v_div_fmas_f32 v12, v12, v38, v39
	v_div_fixup_f32 v12, v12, v13, 1.0
	v_mul_f32_e32 v12, v17, v12
	v_add_f32_e32 v13, 1.0, v19
	v_div_scale_f32 v17, s[0:1], v13, v13, 1.0
	v_rcp_f32_e32 v19, v17
	v_bfe_u32 v38, v12, 16, 1
	v_add3_u32 v12, v12, v38, s21
	global_store_short_d16_hi v[4:5], v12, off offset:128
	v_fma_f32 v12, -v17, v19, 1.0
	v_fmac_f32_e32 v19, v12, v19
	v_div_scale_f32 v12, vcc, 1.0, v13, 1.0
	v_mul_f32_e32 v38, v12, v19
	v_fma_f32 v39, -v17, v38, v12
	v_mul_f32_e32 v11, v11, v3
	v_fmac_f32_e32 v38, v39, v19
	v_fma_f32 v11, v35, v11, v29
	v_fma_f32 v12, -v17, v38, v12
	v_mul_f32_e32 v17, 0xbfb8aa3b, v11
	v_exp_f32_e32 v17, v17
	v_div_fmas_f32 v12, v12, v19, v38
	v_div_fixup_f32 v12, v12, v13, 1.0
	v_mul_f32_e32 v12, v15, v12
	v_add_f32_e32 v13, 1.0, v17
	v_div_scale_f32 v15, s[0:1], v13, v13, 1.0
	v_rcp_f32_e32 v17, v15
	v_bfe_u32 v19, v12, 16, 1
	v_add3_u32 v12, v12, v19, s21
	global_store_short_d16_hi v[4:5], v12, off offset:256
	v_fma_f32 v12, -v15, v17, 1.0
	v_fmac_f32_e32 v17, v12, v17
	v_div_scale_f32 v12, vcc, 1.0, v13, 1.0
	v_mul_f32_e32 v19, v12, v17
	v_fma_f32 v38, -v15, v19, v12
	v_fmac_f32_e32 v19, v38, v17
	v_fma_f32 v12, -v15, v19, v12
	v_mul_f32_e32 v15, v55, v3
	v_fma_f32 v15, v34, v15, v28
	v_mul_f32_e32 v38, 0xbfb8aa3b, v15
	v_exp_f32_e32 v38, v38
	v_div_fmas_f32 v12, v12, v17, v19
	v_div_fixup_f32 v12, v12, v13, 1.0
	v_mul_f32_e32 v11, v11, v12
	v_add_f32_e32 v12, 1.0, v38
	v_div_scale_f32 v13, s[0:1], v12, v12, 1.0
	v_rcp_f32_e32 v17, v13
	v_bfe_u32 v19, v11, 16, 1
	v_add3_u32 v11, v11, v19, s21
	global_store_short_d16_hi v[4:5], v11, off offset:384
	v_fma_f32 v11, -v13, v17, 1.0
	v_fmac_f32_e32 v17, v11, v17
	v_div_scale_f32 v11, vcc, 1.0, v12, 1.0
	v_mul_f32_e32 v19, v11, v17
	v_fma_f32 v38, -v13, v19, v11
	v_fmac_f32_e32 v19, v38, v17
	v_fma_f32 v11, -v13, v19, v11
	v_mul_f32_e32 v13, v54, v3
	v_fma_f32 v13, v30, v13, v25
	v_mul_f32_e32 v38, 0xbfb8aa3b, v13
	v_exp_f32_e32 v38, v38
	v_div_fmas_f32 v11, v11, v17, v19
	v_div_fixup_f32 v11, v11, v12, 1.0
	v_mul_f32_e32 v11, v15, v11
	v_add_f32_e32 v12, 1.0, v38
	v_div_scale_f32 v15, s[0:1], v12, v12, 1.0
	v_rcp_f32_e32 v17, v15
	v_bfe_u32 v19, v11, 16, 1
	v_add3_u32 v11, v11, v19, s21
	global_store_short_d16_hi v[4:5], v11, off offset:512
	v_fma_f32 v11, -v15, v17, 1.0
	v_fmac_f32_e32 v17, v11, v17
	v_div_scale_f32 v11, vcc, 1.0, v12, 1.0
	v_mul_f32_e32 v19, v11, v17
	v_fma_f32 v38, -v15, v19, v11
	v_fmac_f32_e32 v19, v38, v17
	v_fma_f32 v11, -v15, v19, v11
	v_mul_f32_e32 v15, v21, v3
	v_fma_f32 v15, v26, v15, v23
	v_mul_f32_e32 v21, 0xbfb8aa3b, v15
	v_exp_f32_e32 v21, v21
	v_div_fmas_f32 v11, v11, v17, v19
	v_div_fixup_f32 v11, v11, v12, 1.0
	v_mul_f32_e32 v11, v13, v11
	v_add_f32_e32 v12, 1.0, v21
	v_div_scale_f32 v13, s[0:1], v12, v12, 1.0
	v_rcp_f32_e32 v17, v13
	v_bfe_u32 v19, v11, 16, 1
	v_add3_u32 v11, v11, v19, s21
	global_store_short_d16_hi v[4:5], v11, off offset:640
	v_fma_f32 v11, -v13, v17, 1.0
	v_fmac_f32_e32 v17, v11, v17
	v_div_scale_f32 v11, vcc, 1.0, v12, 1.0
	v_mul_f32_e32 v19, v11, v17
	v_fma_f32 v21, -v13, v19, v11
	v_mul_f32_e32 v3, v20, v3
	v_fmac_f32_e32 v19, v21, v17
	v_fma_f32 v3, v24, v3, v22
; DI int half_id() { return __builtin_amdgcn_readfirstlane((int)(threadIdx.x >> 8)); }
; DI void hsync() { hsync_impl(false); }
; DI float sigmoidf_(float x) { return 1.f / (1.f + __expf(-x)); }
; DI void hsync_impl(const bool INIT) {
;     ...
;   asm volatile("s_waitcnt vmcnt(0) lgkmcnt(0)" ::: "memory");
;   if ((threadIdx.x & 63) == 0) {
;     const int h2 = 2 * half_id();
;     const unsigned gen = __hip_atomic_load(&hb[h2 + 1], __ATOMIC_RELAXED, __HIP_MEMORY_SCOPE_WORKGROUP);
;     const unsigned old = __hip_atomic_fetch_add(&hb[h2], 1u, __ATOMIC_RELAXED, __HIP_MEMORY_SCOPE_WORKGROUP);
;     if (old == 3u) {
;       __hip_atomic_store(&hb[h2], 0u, __ATOMIC_RELAXED, __HIP_MEMORY_SCOPE_WORKGROUP);
;       asm volatile("s_waitcnt vmcnt(0) lgkmcnt(0)" ::: "memory");
;       __hip_atomic_fetch_add(&hb[h2 + 1], 1u, __ATOMIC_RELAXED, __HIP_MEMORY_SCOPE_WORKGROUP);
;     } else {
;       while (__hip_atomic_load(&hb[h2 + 1], __ATOMIC_RELAXED, __HIP_MEMORY_SCOPE_WORKGROUP) == gen) __builtin_amdgcn_s_sleep(1);
; DI void conv_item(const Params& p, int item, char* smem) {
;     ...
; #pragma unroll
;     for (int i = 0; i < 8; ++i) {
;       int c = lane + 64 * i;
;       float y = (v[i] - mean) * rstd * p.g_ln[c] + p.b_ln[c];
;       float sl = y * sigmoidf_(y);
;       CACT[((size_t)(b * 4096 + t0 + tl)) * 512 + c] = f2bf(sl);
;     }
;   }
;   hsync();
	v_fma_f32 v11, -v13, v19, v11
	v_mul_f32_e32 v13, 0xbfb8aa3b, v3
	v_exp_f32_e32 v13, v13
	v_div_fmas_f32 v11, v11, v17, v19
	v_div_fixup_f32 v11, v11, v12, 1.0
	v_mul_f32_e32 v11, v15, v11
	v_add_f32_e32 v12, 1.0, v13
	v_div_scale_f32 v13, s[0:1], v12, v12, 1.0
	v_rcp_f32_e32 v15, v13
	v_bfe_u32 v17, v11, 16, 1
	v_add3_u32 v11, v11, v17, s21
	global_store_short_d16_hi v[4:5], v11, off offset:768
	v_fma_f32 v11, -v13, v15, 1.0
	v_fmac_f32_e32 v15, v11, v15
	v_div_scale_f32 v11, vcc, 1.0, v12, 1.0
	v_mul_f32_e32 v17, v11, v15
	v_fma_f32 v19, -v13, v17, v11
	v_fmac_f32_e32 v17, v19, v15
	v_fma_f32 v11, -v13, v17, v11
	v_div_fmas_f32 v11, v11, v15, v17
	v_mul_f32_e32 v13, 0x4b800000, v2
	v_cmp_gt_f32_e32 vcc, s20, v2
	v_div_fixup_f32 v11, v11, v12, 1.0
	v_mul_f32_e32 v3, v3, v11
	v_cndmask_b32_e32 v2, v2, v13, vcc
	v_rsq_f32_e32 v2, v2
	v_bfe_u32 v11, v3, 16, 1
	v_mul_f32_e32 v12, 0x45800000, v2
	v_cndmask_b32_e32 v12, v2, v12, vcc
	v_mul_f32_e32 v2, v18, v12
	v_fmac_f32_e32 v32, v36, v2
	v_mul_f32_e32 v2, 0xbfb8aa3b, v32
	v_exp_f32_e32 v13, v2
	v_add3_u32 v2, v3, v11, s21
	global_store_short_d16_hi v[4:5], v2, off offset:896
	v_add_u32_e32 v2, s12, v62
	v_add_f32_e32 v4, 1.0, v13
	v_div_scale_f32 v5, s[0:1], v4, v4, 1.0
	v_rcp_f32_e32 v11, v5
	v_ashrrev_i32_e32 v3, 31, v2
	v_lshlrev_b64 v[2:3], 10, v[2:3]
	v_lshl_add_u64 v[2:3], s[6:7], 0, v[2:3]
	v_fma_f32 v13, -v5, v11, 1.0
	v_fmac_f32_e32 v11, v13, v11
	v_div_scale_f32 v13, vcc, 1.0, v4, 1.0
	v_mul_f32_e32 v15, v13, v11
	v_fma_f32 v17, -v5, v15, v13
	v_fmac_f32_e32 v15, v17, v11
	v_fma_f32 v5, -v5, v15, v13
	v_div_fmas_f32 v5, v5, v11, v15
	v_mul_f32_e32 v11, v16, v12
	v_fmac_f32_e32 v27, v33, v11
	v_mul_f32_e32 v11, 0xbfb8aa3b, v27
	v_exp_f32_e32 v11, v11
	v_div_fixup_f32 v4, v5, v4, 1.0
	v_mul_f32_e32 v4, v32, v4
	v_bfe_u32 v5, v4, 16, 1
	v_add_f32_e32 v11, 1.0, v11
	v_div_scale_f32 v13, s[0:1], v11, v11, 1.0
	v_rcp_f32_e32 v15, v13
	v_lshl_add_u64 v[2:3], v[2:3], 0, v[0:1]
	v_add3_u32 v4, v4, v5, s21
	global_store_short_d16_hi v[2:3], v4, off
	v_fma_f32 v0, -v13, v15, 1.0
	v_fmac_f32_e32 v15, v0, v15
	v_div_scale_f32 v0, vcc, 1.0, v11, 1.0
	v_mul_f32_e32 v4, v0, v15
	v_fma_f32 v5, -v13, v4, v0
	v_fmac_f32_e32 v4, v5, v15
	v_mul_f32_e32 v5, v14, v12
	v_fmac_f32_e32 v31, v37, v5
	v_mul_f32_e32 v5, 0xbfb8aa3b, v31
	v_exp_f32_e32 v5, v5
	v_fma_f32 v0, -v13, v4, v0
	v_div_fmas_f32 v0, v0, v15, v4
	v_div_fixup_f32 v0, v0, v11, 1.0
	v_add_f32_e32 v4, 1.0, v5
	v_div_scale_f32 v5, s[0:1], v4, v4, 1.0
	v_rcp_f32_e32 v11, v5
	v_mul_f32_e32 v0, v27, v0
	v_bfe_u32 v13, v0, 16, 1
	v_add3_u32 v0, v0, v13, s21
	global_store_short_d16_hi v[2:3], v0, off offset:128
	v_fma_f32 v0, -v5, v11, 1.0
	v_fmac_f32_e32 v11, v0, v11
	v_div_scale_f32 v0, vcc, 1.0, v4, 1.0
	v_mul_f32_e32 v13, v0, v11
	v_fma_f32 v14, -v5, v13, v0
	v_fmac_f32_e32 v13, v14, v11
	v_fma_f32 v0, -v5, v13, v0
	v_mul_f32_e32 v5, v10, v12
	v_fmac_f32_e32 v29, v35, v5
	v_mul_f32_e32 v5, 0xbfb8aa3b, v29
	v_exp_f32_e32 v5, v5
	v_div_fmas_f32 v0, v0, v11, v13
	v_div_fixup_f32 v0, v0, v4, 1.0
	v_mul_f32_e32 v0, v31, v0
	v_add_f32_e32 v4, 1.0, v5
	v_div_scale_f32 v5, s[0:1], v4, v4, 1.0
	v_rcp_f32_e32 v10, v5
	v_bfe_u32 v11, v0, 16, 1
	v_add3_u32 v0, v0, v11, s21
	global_store_short_d16_hi v[2:3], v0, off offset:256
	v_fma_f32 v0, -v5, v10, 1.0
	v_fmac_f32_e32 v10, v0, v10
	v_div_scale_f32 v0, vcc, 1.0, v4, 1.0
	v_mul_f32_e32 v11, v0, v10
	v_fma_f32 v13, -v5, v11, v0
	v_fmac_f32_e32 v11, v13, v10
	v_fma_f32 v0, -v5, v11, v0
	v_mul_f32_e32 v5, v9, v12
	v_fmac_f32_e32 v28, v34, v5
	v_mul_f32_e32 v5, 0xbfb8aa3b, v28
	v_exp_f32_e32 v5, v5
	v_div_fmas_f32 v0, v0, v10, v11
	v_div_fixup_f32 v0, v0, v4, 1.0
	v_mul_f32_e32 v0, v29, v0
	v_add_f32_e32 v4, 1.0, v5
	v_div_scale_f32 v5, s[0:1], v4, v4, 1.0
	v_rcp_f32_e32 v9, v5
	v_bfe_u32 v10, v0, 16, 1
	v_add3_u32 v0, v0, v10, s21
	global_store_short_d16_hi v[2:3], v0, off offset:384
	v_fma_f32 v0, -v5, v9, 1.0
	v_fmac_f32_e32 v9, v0, v9
	v_div_scale_f32 v0, vcc, 1.0, v4, 1.0
	v_mul_f32_e32 v10, v0, v9
	v_fma_f32 v11, -v5, v10, v0
	v_fmac_f32_e32 v10, v11, v9
	v_fma_f32 v0, -v5, v10, v0
	v_mul_f32_e32 v5, v8, v12
	v_fmac_f32_e32 v25, v30, v5
	v_mul_f32_e32 v5, 0xbfb8aa3b, v25
	v_exp_f32_e32 v5, v5
	v_div_fmas_f32 v0, v0, v9, v10
	v_div_fixup_f32 v0, v0, v4, 1.0
	v_mul_f32_e32 v0, v28, v0
	v_add_f32_e32 v4, 1.0, v5
	v_div_scale_f32 v5, s[0:1], v4, v4, 1.0
	v_rcp_f32_e32 v8, v5
	v_bfe_u32 v9, v0, 16, 1
	v_add3_u32 v0, v0, v9, s21
	global_store_short_d16_hi v[2:3], v0, off offset:512
	v_fma_f32 v0, -v5, v8, 1.0
	v_fmac_f32_e32 v8, v0, v8
	v_div_scale_f32 v0, vcc, 1.0, v4, 1.0
	v_mul_f32_e32 v9, v0, v8
	v_fma_f32 v10, -v5, v9, v0
	v_fmac_f32_e32 v9, v10, v8
	v_fma_f32 v0, -v5, v9, v0
	v_mul_f32_e32 v5, v7, v12
	v_fmac_f32_e32 v23, v26, v5
	v_mul_f32_e32 v5, 0xbfb8aa3b, v23
	v_exp_f32_e32 v5, v5
	v_div_fmas_f32 v0, v0, v8, v9
	v_div_fixup_f32 v0, v0, v4, 1.0
	v_mul_f32_e32 v0, v25, v0
	v_add_f32_e32 v4, 1.0, v5
	v_div_scale_f32 v5, s[0:1], v4, v4, 1.0
	v_rcp_f32_e32 v7, v5
	v_bfe_u32 v8, v0, 16, 1
	v_add3_u32 v0, v0, v8, s21
	global_store_short_d16_hi v[2:3], v0, off offset:640
	v_fma_f32 v0, -v5, v7, 1.0
	v_fmac_f32_e32 v7, v0, v7
	v_div_scale_f32 v0, vcc, 1.0, v4, 1.0
	v_mul_f32_e32 v8, v0, v7
	v_fma_f32 v9, -v5, v8, v0
	v_fmac_f32_e32 v8, v9, v7
	v_fma_f32 v0, -v5, v8, v0
	v_mul_f32_e32 v5, v6, v12
	v_fmac_f32_e32 v22, v24, v5
	v_mul_f32_e32 v5, 0xbfb8aa3b, v22
	v_exp_f32_e32 v5, v5
	v_div_fmas_f32 v0, v0, v7, v8
	v_div_fixup_f32 v0, v0, v4, 1.0
	v_mul_f32_e32 v0, v23, v0
	v_add_f32_e32 v4, 1.0, v5
	v_div_scale_f32 v5, s[0:1], v4, v4, 1.0
	v_rcp_f32_e32 v6, v5
	v_bfe_u32 v7, v0, 16, 1
	v_add3_u32 v0, v0, v7, s21
	global_store_short_d16_hi v[2:3], v0, off offset:768
	v_fma_f32 v0, -v5, v6, 1.0
	v_fmac_f32_e32 v6, v0, v6
	v_div_scale_f32 v0, vcc, 1.0, v4, 1.0
	v_mul_f32_e32 v7, v0, v6
	v_fma_f32 v8, -v5, v7, v0
	v_fmac_f32_e32 v7, v8, v6
	v_fma_f32 v0, -v5, v7, v0
	v_div_fmas_f32 v0, v0, v6, v7
	v_div_fixup_f32 v0, v0, v4, 1.0
	v_mul_f32_e32 v0, v22, v0
	v_bfe_u32 v4, v0, 16, 1
	v_add3_u32 v0, v0, v4, s21
	global_store_short_d16_hi v[2:3], v0, off offset:896
	s_waitcnt vmcnt(0) lgkmcnt(0)
	s_and_saveexec_b64 s[0:1], s[4:5]
	s_cbranch_execz .LBB0_660
	v_readfirstlane_b32 s14, v211
	s_lshr_b32 s14, s14, 5
	s_and_b32 s16, s14, 0x7fffff8
	v_mov_b32_e32 v0, s16
	ds_read_b32 v0, v0 offset:4
	s_mov_b64 s[12:13], exec
	v_mbcnt_lo_u32_b32 v2, s12, 0
	v_mbcnt_hi_u32_b32 v2, s13, v2
	v_cmp_eq_u32_e32 vcc, 0, v2
	s_and_saveexec_b64 s[14:15], vcc
	s_bcnt1_i32_b64 s12, s[12:13]
	v_mov_b32_e32 v3, s16
	v_mov_b32_e32 v4, s12
	ds_add_rtn_u32 v3, v3, v4
	s_or_b64 exec, exec, s[14:15]
	s_waitcnt lgkmcnt(0)
	v_readfirstlane_b32 s12, v3
	s_nop 1
	v_add_u32_e32 v2, s12, v2
	v_cmp_ne_u32_e32 vcc, 3, v2
	s_and_saveexec_b64 s[12:13], vcc
	s_xor_b64 s[12:13], exec, s[12:13]
	s_cbranch_execz .LBB0_749
	v_mov_b32_e32 v2, s16
	ds_read_b32 v2, v2 offset:4
	s_waitcnt lgkmcnt(0)
	v_cmp_ne_u32_e32 vcc, v2, v0
	s_cbranch_vccnz .LBB0_749
